# final RMSNorm rows stored write-through (sc1): less dirty L2 left to write back at kernel end
# baseline (speedup 1.0000x reference)
; __device__ __forceinline__ float red64(float x) { x = red16(x); x += __shfl_xor(x, 16); x += __shfl_xor(x, 32); return x; }
; __device__ __forceinline__ void ph_final(const Params& p) {
;     ...
;     for (; row < NTOK; row += nw) {
;         const int nr = row + nw;
;         if (nr < NTOK) { const f32x4* x = (const f32x4*)(p.out + (size_t)nr * D);
; #pragma unroll
;             for (int i = 0; i < 4; ++i) nxt[i] = x[i * 64 + lane]; }
;         float ss = 0.f;
; #pragma unroll
;         for (int i = 0; i < 4; ++i) ss += (cur[i][0] * cur[i][0] + cur[i][1] * cur[i][1]) + (cur[i][2] * cur[i][2] + cur[i][3] * cur[i][3]);
;         ss = red64(ss); const float rs = rsqrtf(ss * (1.0f / 1024.0f) + 1e-6f);
;         f32x4* xo = (f32x4*)(p.out + (size_t)row * D);
; #pragma unroll
;         for (int i = 0; i < 4; ++i) xo[i * 64 + lane] = cur[i] * rs * gn[i];
; #pragma unroll
;         for (int i = 0; i < 4; ++i) cur[i] = nxt[i];
;     }
.LBB0_1436:
	s_or_b64 exec, exec, s[8:9]
	s_waitcnt vmcnt(3)
	v_pk_mul_f32 v[62:63], v[30:31], v[30:31]
	v_pk_mul_f32 v[64:65], v[28:29], v[28:29]
	s_waitcnt vmcnt(2)
	v_pk_mul_f32 v[58:59], v[26:27], v[26:27]
	v_pk_mul_f32 v[60:61], v[24:25], v[24:25]
	v_pk_mov_b32 v[66:67], v[64:65], v[62:63] op_sel:[1,0]
	v_mov_b32_e32 v65, v63
	v_pk_add_f32 v[62:63], v[66:67], v[64:65]
	v_pk_mov_b32 v[64:65], v[60:61], v[58:59] op_sel:[1,0]
	v_mov_b32_e32 v61, v59
	v_pk_add_f32 v[58:59], v[64:65], v[60:61]
	v_pk_add_f32 v[62:63], v[62:63], v[62:63] op_sel_hi:[0,1]
	v_pk_add_f32 v[58:59], v[58:59], v[58:59] op_sel_hi:[0,1]
	s_waitcnt vmcnt(1)
	v_mul_f32_e32 v58, v20, v20
	v_pk_fma_f32 v[60:61], v[20:21], v[20:21], v[58:59] op_sel_hi:[1,1,0]
	v_mul_f32_e32 v58, v22, v22
	v_pk_fma_f32 v[64:65], v[22:23], v[22:23], v[58:59] op_sel_hi:[1,1,0]
	s_waitcnt vmcnt(0)
	v_mul_f32_e32 v60, v16, v16
	v_mul_f32_e32 v64, v17, v17
	v_mul_f32_e32 v62, v18, v18
	v_mul_f32_e32 v58, v19, v19
	v_pk_add_f32 v[60:61], v[60:61], v[64:65]
	v_pk_add_f32 v[58:59], v[62:63], v[58:59]
	s_and_b64 s[8:9], exec, vcc
	v_pk_add_f32 v[58:59], v[60:61], v[58:59]
	v_lshl_add_u64 v[60:61], v[52:53], 0, v[50:51]
	v_add_f32_e32 v58, v58, v59
	s_or_b64 s[6:7], s[8:9], s[6:7]
	v_lshl_add_u64 v[52:53], v[52:53], 0, s[4:5]
	v_add_f32_dpp v58, v58, v58 quad_perm:[1,0,3,2] row_mask:0xf bank_mask:0xf bound_ctrl:1
	v_lshl_add_u64 v[54:55], v[54:55], 0, s[4:5]
	s_nop 0
	v_add_f32_dpp v58, v58, v58 quad_perm:[2,3,0,1] row_mask:0xf bank_mask:0xf bound_ctrl:1
	s_nop 1
	v_add_f32_dpp v58, v58, v58 row_half_mirror row_mask:0xf bank_mask:0xf bound_ctrl:1
	s_nop 1
	v_add_f32_dpp v58, v58, v58 row_mirror row_mask:0xf bank_mask:0xf bound_ctrl:1
	ds_bpermute_b32 v59, v49, v58
	s_waitcnt lgkmcnt(0)
	v_add_f32_e32 v58, v58, v59
	ds_bpermute_b32 v59, v56, v58
	s_waitcnt lgkmcnt(0)
	v_add_f32_e32 v58, v58, v59
	v_fmamk_f32 v58, v58, 0x3a800000, v57
	v_mul_f32_e32 v59, 0x4b800000, v58
	v_cmp_gt_f32_e64 s[0:1], s11, v58
	s_nop 1
	v_cndmask_b32_e64 v58, v58, v59, s[0:1]
	v_rsq_f32_e32 v58, v58
	s_nop 0
	v_mul_f32_e32 v59, 0x45800000, v58
	v_cndmask_b32_e64 v58, v58, v59, s[0:1]
	v_pk_mul_f32 v[28:29], v[28:29], v[58:59] op_sel_hi:[1,0]
	v_pk_mul_f32 v[30:31], v[30:31], v[58:59] op_sel_hi:[1,0]
	v_pk_mul_f32 v[24:25], v[24:25], v[58:59] op_sel_hi:[1,0]
	v_pk_mul_f32 v[26:27], v[26:27], v[58:59] op_sel_hi:[1,0]
	v_pk_mul_f32 v[20:21], v[20:21], v[58:59] op_sel_hi:[1,0]
	v_pk_mul_f32 v[22:23], v[22:23], v[58:59] op_sel_hi:[1,0]
	v_pk_mul_f32 v[16:17], v[16:17], v[58:59] op_sel_hi:[1,0]
	v_pk_mul_f32 v[18:19], v[18:19], v[58:59] op_sel_hi:[1,0]
	v_pk_mul_f32 v[30:31], v[2:3], v[30:31]
	v_pk_mul_f32 v[28:29], v[0:1], v[28:29]
	v_pk_mul_f32 v[26:27], v[6:7], v[26:27]
	v_pk_mul_f32 v[24:25], v[4:5], v[24:25]
	v_pk_mul_f32 v[22:23], v[10:11], v[22:23]
	v_pk_mul_f32 v[20:21], v[8:9], v[20:21]
	v_pk_mul_f32 v[18:19], v[14:15], v[18:19]
	v_pk_mul_f32 v[16:17], v[12:13], v[16:17]
	global_store_dwordx4 v[60:61], v[28:31], off sc1
	global_store_dwordx4 v[60:61], v[24:27], off offset:1024 sc1
	global_store_dwordx4 v[60:61], v[20:23], off offset:2048 sc1
	global_store_dwordx4 v[60:61], v[16:19], off offset:3072 sc1
	v_mov_b32_e32 v28, v32
	v_mov_b32_e32 v29, v33
	v_mov_b32_e32 v30, v34
	v_mov_b32_e32 v31, v35
	v_mov_b32_e32 v24, v36
	v_mov_b32_e32 v25, v37
	v_mov_b32_e32 v26, v38
	v_mov_b32_e32 v27, v39
	v_mov_b32_e32 v20, v40
	v_mov_b32_e32 v21, v41
	v_mov_b32_e32 v22, v42
	v_mov_b32_e32 v23, v43
	v_mov_b32_e32 v16, v44
	v_mov_b32_e32 v17, v45
	v_mov_b32_e32 v18, v46
	v_mov_b32_e32 v19, v47
	s_andn2_b64 exec, exec, s[6:7]
	s_cbranch_execz .LBB0_1439
